# v058 + rcp+Newton silu division chains in the generic (POOL-mode) GEMM epilogue loop - step 3 third round is all POOL tiles
# speedup vs baseline: 1.0041x; 1.0012x over previous
; DEVI float bf2f(u16 h) { return __uint_as_float(((unsigned)h) << 16); }
; DEVI float bfs(short h) { return __uint_as_float(((unsigned)(u16)h) << 16); }
; DEVI float silu_f(float x) { return x / (1.f + __expf(-x)); }
; DEVI void gemm256(const P& p, const u16* A, int lda, const u16* Bt, int ldb, int K, int brow, int bcol, int mode,
;                         int aux, int layer, int bmode) {
;     ...
;     for (int it = 0; it < 16; ++it) {
;       const int R = it * 16 + (tid >> 5), c = tid & 31;
;       if ((c < 16) ? tr0 : tr1) continue;
;       const int row = brow + R, col = bcol + c * 8;
;       bf16x8 raw = *(const bf16x8*)(stg + R * 256 + SWZ(R, c) * 8);
;       if (mode == M_G1A) {
;         *(bf16x8*)((u16*)(ws + O_PROJ) + (size_t)row * NP + col) = raw;
;       } else if (mode == M_G4) {
;         *(bf16x8*)((u16*)(ws + O_YBR) + (size_t)row * 8192 + aux * 2048 + col) = raw;
;       } else {
;         float v[8];
; #pragma unroll
;         for (int e = 0; e < 8; ++e) v[e] = bfs(raw[e]);
;         if (mode == M_G2) {
;           float rs = ((const float*)(ws + O_RINV))[row * 2];
; #pragma unroll
;           for (int e = 0; e < 8; ++e) v[e] *= rs;
;           st8((u16*)(ws + O_QH) + (size_t)row * 768 + col, v);
;         } else if (mode == M_G3) {
;           float rs = ((const float*)(ws + O_RINV))[row * 2 + 1];
; #pragma unroll
;           for (int e = 0; e < 8; ++e) v[e] *= rs;
;           st8((u16*)(ws + O_KH) + ((size_t)(bb * 4 + (col >> 8)) * TPB + (trow + R)) * 192 + (col & 255), v);
;         } else if (mode == M_POOL) {
;           float g[8];
;           ld8((const u16*)(ws + O_PROJ) + (size_t)row * NP + C_BG + col, g);
; #pragma unroll
;           for (int e = 0; e < 8; ++e) {
;             float y = bf2f(f2bf(v[e] * p.pool_scale[layer * 512 + col + e]));
;             v[e] = y * silu_f(g[e]);
;           }
;           st8((u16*)(ws + O_YS) + (size_t)row * 2048 + 512 + col, v);
.LBB0_198:
	s_lshl_b32 s51, s50, 4
	s_and_saveexec_b64 s[34:35], s[82:83]
	s_cbranch_execz .LBB0_249
	s_waitcnt lgkmcnt(0)
	ds_read_b128 v[2:5], v0
	s_mov_b64 s[2:3], -1
	s_and_b64 vcc, exec, s[0:1]
	s_cbranch_vccz .LBB0_222
	s_and_b64 vcc, exec, s[78:79]
	s_cbranch_vccz .LBB0_219
	s_waitcnt lgkmcnt(0)
	v_and_b32_e32 v45, 0xffff0000, v2
	v_lshlrev_b32_e32 v44, 16, v2
	v_and_b32_e32 v47, 0xffff0000, v3
	v_lshlrev_b32_e32 v46, 16, v3
	v_and_b32_e32 v49, 0xffff0000, v4
	v_lshlrev_b32_e32 v48, 16, v4
	v_and_b32_e32 v51, 0xffff0000, v5
	v_lshlrev_b32_e32 v50, 16, v5
	s_mov_b64 s[76:77], -1
	s_mov_b64 s[36:37], 0
	s_cmp_lt_i32 s71, 2
	s_mov_b64 s[2:3], 0
	s_cbranch_scc1 .LBB0_214
	s_cmp_gt_i32 s71, 2
	s_cbranch_scc0 .LBB0_206
	s_cmp_eq_u32 s71, 3
	s_mov_b64 s[2:3], -1
	s_cbranch_scc0 .LBB0_205
	v_mov_b64_e32 v[6:7], s[80:81]
	s_movk_i32 s2, 0x3a00
	v_mad_i64_i32 v[62:63], s[2:3], v36, s2, v[6:7]
	v_lshl_add_u64 v[6:7], v[62:63], 0, v[16:17]
	v_add_co_u32_e32 v6, vcc, 0xa28b000, v6
	s_movk_i32 s2, 0xd600
	s_nop 0
	v_addc_co_u32_e32 v7, vcc, 0, v7, vcc
	global_load_dwordx4 v[6:9], v[6:7], off offset:1024
	s_nop 0
	global_load_dwordx4 v[52:55], v[30:31], off offset:16
	global_load_dwordx4 v[56:59], v[30:31], off
	s_waitcnt vmcnt(2)
	v_and_b32_e32 v11, 0xffff0000, v6
	v_lshlrev_b32_e32 v6, 16, v6
	s_waitcnt vmcnt(0)
	v_pk_mul_f32 v[56:57], v[56:57], v[44:45]
	v_mul_f32_e32 v37, 0xbfb8aa3b, v6
	v_pk_mul_f32 v[60:61], v[58:59], v[46:47]
	v_pk_mul_f32 v[58:59], v[52:53], v[48:49]
	v_mad_i64_i32 v[52:53], s[2:3], v36, s2, v[62:63]
	v_exp_f32_e32 v62, v37
	v_and_b32_sdwa v37, v57, v195 dst_sel:DWORD dst_unused:UNUSED_PAD src0_sel:WORD_1 src1_sel:DWORD
	v_add3_u32 v37, v57, v37, s33
	v_and_b32_e32 v57, 0xffff0000, v37
	v_mul_f32_e32 v37, 0xbfb8aa3b, v11
	v_exp_f32_e32 v63, v37
	v_and_b32_sdwa v39, v56, v195 dst_sel:DWORD dst_unused:UNUSED_PAD src0_sel:WORD_1 src1_sel:DWORD
	v_add3_u32 v39, v56, v39, s33
	v_and_b32_e32 v56, 0xffff0000, v39
	v_pk_add_f32 v[62:63], v[62:63], 1.0 op_sel_hi:[1,0]
	v_pk_mul_f32 v[54:55], v[54:55], v[50:51]
	v_rcp_f32_e32 v37, v63
	s_nop 0
	v_lshl_add_u64 v[52:53], v[52:53], 0, v[16:17]
	v_fma_f32 v66, -v63, v37, 1.0
	v_fma_f32 v37, v66, v37, v37
	v_mul_f32_e32 v63, v11, v37
	v_rcp_f32_e32 v11, v62
	s_nop 0
	s_nop 0
	v_fma_f32 v39, -v62, v11, 1.0
	v_fma_f32 v11, v39, v11, v11
	v_mul_f32_e32 v62, v6, v11
	v_and_b32_e32 v11, 0xffff0000, v7
	v_lshlrev_b32_e32 v37, 16, v7
	v_and_b32_sdwa v7, v61, v195 dst_sel:DWORD dst_unused:UNUSED_PAD src0_sel:WORD_1 src1_sel:DWORD
	v_add3_u32 v7, v61, v7, s33
	v_mul_f32_e32 v6, 0xbfb8aa3b, v37
	v_and_b32_e32 v61, 0xffff0000, v7
	v_mul_f32_e32 v7, 0xbfb8aa3b, v11
	v_exp_f32_e32 v6, v6
	v_exp_f32_e32 v7, v7
	v_and_b32_sdwa v39, v60, v195 dst_sel:DWORD dst_unused:UNUSED_PAD src0_sel:WORD_1 src1_sel:DWORD
	v_add3_u32 v39, v60, v39, s33
	v_and_b32_e32 v60, 0xffff0000, v39
	v_pk_add_f32 v[6:7], v[6:7], 1.0 op_sel_hi:[1,0]
	v_pk_mul_f32 v[56:57], v[62:63], v[56:57]
	v_rcp_f32_e32 v39, v7
	s_nop 0
	s_nop 0
	v_fma_f32 v63, -v7, v39, 1.0
	v_fma_f32 v39, v63, v39, v39
	v_mul_f32_e32 v7, v11, v39
	v_rcp_f32_e32 v11, v6
	s_nop 0
	s_nop 0
	v_fma_f32 v62, -v6, v11, 1.0
	v_fma_f32 v11, v62, v11, v11
	v_mul_f32_e32 v6, v37, v11
	v_and_b32_e32 v11, 0xffff0000, v8
	v_lshlrev_b32_e32 v8, 16, v8
	v_mul_f32_e32 v37, 0xbfb8aa3b, v8
	v_pk_mul_f32 v[6:7], v[6:7], v[60:61]
	v_exp_f32_e32 v60, v37
	v_and_b32_sdwa v37, v59, v195 dst_sel:DWORD dst_unused:UNUSED_PAD src0_sel:WORD_1 src1_sel:DWORD
	v_add3_u32 v37, v59, v37, s33
	v_and_b32_e32 v59, 0xffff0000, v37
	v_mul_f32_e32 v37, 0xbfb8aa3b, v11
	v_exp_f32_e32 v61, v37
	v_and_b32_sdwa v39, v58, v195 dst_sel:DWORD dst_unused:UNUSED_PAD src0_sel:WORD_1 src1_sel:DWORD
	v_add3_u32 v39, v58, v39, s33
	v_and_b32_e32 v58, 0xffff0000, v39
	v_pk_add_f32 v[60:61], v[60:61], 1.0 op_sel_hi:[1,0]
	s_nop 0
	v_rcp_f32_e32 v37, v61
	s_nop 0
	s_nop 0
	v_fma_f32 v62, -v61, v37, 1.0
	v_fma_f32 v37, v62, v37, v37
	v_mul_f32_e32 v61, v11, v37
	v_rcp_f32_e32 v11, v60
	s_nop 0
	s_nop 0
	v_fma_f32 v39, -v60, v11, 1.0
	v_fma_f32 v11, v39, v11, v11
	v_mul_f32_e32 v60, v8, v11
	v_and_b32_e32 v11, 0xffff0000, v9
	v_lshlrev_b32_e32 v37, 16, v9
	v_and_b32_sdwa v9, v55, v195 dst_sel:DWORD dst_unused:UNUSED_PAD src0_sel:WORD_1 src1_sel:DWORD
	v_add3_u32 v9, v55, v9, s33
	v_mul_f32_e32 v8, 0xbfb8aa3b, v37
	v_and_b32_e32 v55, 0xffff0000, v9
	v_mul_f32_e32 v9, 0xbfb8aa3b, v11
	v_exp_f32_e32 v8, v8
	v_exp_f32_e32 v9, v9
	v_and_b32_sdwa v39, v54, v195 dst_sel:DWORD dst_unused:UNUSED_PAD src0_sel:WORD_1 src1_sel:DWORD
	v_add3_u32 v39, v54, v39, s33
	v_and_b32_e32 v54, 0xffff0000, v39
	v_pk_add_f32 v[8:9], v[8:9], 1.0 op_sel_hi:[1,0]
	v_pk_mul_f32 v[58:59], v[60:61], v[58:59]
	v_rcp_f32_e32 v39, v9
	s_nop 0
	s_nop 0
	v_fma_f32 v61, -v9, v39, 1.0
	v_fma_f32 v39, v61, v39, v39
	v_mul_f32_e32 v9, v11, v39
	v_rcp_f32_e32 v11, v8
	s_nop 0
	s_mov_b64 s[2:3], 0
	v_fma_f32 v60, -v8, v11, 1.0
	v_fma_f32 v11, v60, v11, v11
	v_mul_f32_e32 v8, v37, v11
	v_pk_mul_f32 v[8:9], v[8:9], v[54:55]
	v_bfe_u32 v39, v59, 16, 1
	v_bfe_u32 v11, v9, 16, 1
	v_bfe_u32 v37, v8, 16, 1
	v_bfe_u32 v54, v58, 16, 1
	v_bfe_u32 v55, v7, 16, 1
	v_bfe_u32 v60, v6, 16, 1
	v_bfe_u32 v61, v57, 16, 1
	v_bfe_u32 v62, v56, 16, 1
	v_add3_u32 v56, v56, v62, s33
	v_add3_u32 v57, v57, v61, s33
	v_add3_u32 v6, v6, v60, s33
	v_add3_u32 v7, v7, v55, s33
	v_add3_u32 v54, v58, v54, s33
	v_add3_u32 v39, v59, v39, s33
	v_add3_u32 v8, v8, v37, s33
	v_add3_u32 v9, v9, v11, s33
	v_add_co_u32_e32 v52, vcc, 0x2223c000, v52
	v_perm_b32 v9, v9, v8, s27
	v_perm_b32 v8, v39, v54, s27
	v_perm_b32 v7, v7, v6, s27
	v_perm_b32 v6, v57, v56, s27
	v_addc_co_u32_e32 v53, vcc, 0, v53, vcc
	global_store_dwordx4 v[52:53], v[6:9], off offset:1024

; DEVI float bf2f(u16 h) { return __uint_as_float(((unsigned)h) << 16); }
; DEVI float bfs(short h) { return __uint_as_float(((unsigned)(u16)h) << 16); }
; DEVI float silu_f(float x) { return x / (1.f + __expf(-x)); }
; DEVI void gemm256(const P& p, const u16* A, int lda, const u16* Bt, int ldb, int K, int brow, int bcol, int mode,
;                         int aux, int layer, int bmode) {
;     ...
;     for (int it = 0; it < 16; ++it) {
;       const int R = it * 16 + (tid >> 5), c = tid & 31;
;       if ((c < 16) ? tr0 : tr1) continue;
;       const int row = brow + R, col = bcol + c * 8;
;       bf16x8 raw = *(const bf16x8*)(stg + R * 256 + SWZ(R, c) * 8);
;       if (mode == M_G1A) {
;         *(bf16x8*)((u16*)(ws + O_PROJ) + (size_t)row * NP + col) = raw;
;       } else if (mode == M_G4) {
;         *(bf16x8*)((u16*)(ws + O_YBR) + (size_t)row * 8192 + aux * 2048 + col) = raw;
;       } else {
;         float v[8];
; #pragma unroll
;         for (int e = 0; e < 8; ++e) v[e] = bfs(raw[e]);
;         if (mode == M_G2) {
;           float rs = ((const float*)(ws + O_RINV))[row * 2];
; #pragma unroll
;           for (int e = 0; e < 8; ++e) v[e] *= rs;
;           st8((u16*)(ws + O_QH) + (size_t)row * 768 + col, v);
;         } else if (mode == M_G3) {
;           float rs = ((const float*)(ws + O_RINV))[row * 2 + 1];
; #pragma unroll
;           for (int e = 0; e < 8; ++e) v[e] *= rs;
;           st8((u16*)(ws + O_KH) + ((size_t)(bb * 4 + (col >> 8)) * TPB + (trow + R)) * 192 + (col & 255), v);
;         } else if (mode == M_POOL) {
;           float g[8];
;           ld8((const u16*)(ws + O_PROJ) + (size_t)row * NP + C_BG + col, g);
; #pragma unroll
;           for (int e = 0; e < 8; ++e) {
;             float y = bf2f(f2bf(v[e] * p.pool_scale[layer * 512 + col + e]));
;             v[e] = y * silu_f(g[e]);
;           }
;           st8((u16*)(ws + O_YS) + (size_t)row * 2048 + 512 + col, v);
.LBB0_224:
	s_waitcnt lgkmcnt(0)
	ds_read_b128 v[2:5], v0 offset:8192
	v_add_u32_e32 v44, 16, v36
	s_and_b64 vcc, exec, s[40:41]
	s_mov_b64 s[2:3], -1
	s_cbranch_vccnz .LBB0_247
	s_andn2_b64 vcc, exec, s[78:79]
	s_cbranch_vccnz .LBB0_244
	s_waitcnt lgkmcnt(0)
	v_and_b32_e32 v47, 0xffff0000, v2
	v_lshlrev_b32_e32 v46, 16, v2
	v_and_b32_e32 v49, 0xffff0000, v3
	v_lshlrev_b32_e32 v48, 16, v3
	v_and_b32_e32 v51, 0xffff0000, v4
	v_lshlrev_b32_e32 v50, 16, v4
	v_and_b32_e32 v53, 0xffff0000, v5
	v_lshlrev_b32_e32 v52, 16, v5
	s_mov_b64 s[76:77], -1
	s_mov_b64 s[36:37], 0
	s_cmp_lt_i32 s71, 2
	s_mov_b64 s[2:3], 0
	s_cbranch_scc1 .LBB0_239
	s_cmp_gt_i32 s71, 2
	s_cbranch_scc0 .LBB0_231
	s_cmp_eq_u32 s71, 3
	s_mov_b64 s[2:3], -1
	s_cbranch_scc0 .LBB0_230
	v_mov_b64_e32 v[6:7], s[80:81]
	s_movk_i32 s2, 0x3a00
	v_mad_i64_i32 v[66:67], s[2:3], v44, s2, v[6:7]
	v_lshl_add_u64 v[6:7], v[66:67], 0, v[16:17]
	v_add_co_u32_e32 v6, vcc, 0xa28b000, v6
	s_movk_i32 s2, 0xd600
	s_nop 0
	v_addc_co_u32_e32 v7, vcc, 0, v7, vcc
	global_load_dwordx4 v[6:9], v[6:7], off offset:1024
	s_nop 0
	global_load_dwordx4 v[54:57], v[30:31], off offset:16
	global_load_dwordx4 v[58:61], v[30:31], off
	s_waitcnt vmcnt(2)
	v_and_b32_e32 v11, 0xffff0000, v6
	v_lshlrev_b32_e32 v6, 16, v6
	s_waitcnt vmcnt(0)
	v_pk_mul_f32 v[58:59], v[58:59], v[46:47]
	v_mul_f32_e32 v37, 0xbfb8aa3b, v6
	v_pk_mul_f32 v[62:63], v[60:61], v[48:49]
	v_pk_mul_f32 v[60:61], v[54:55], v[50:51]
	v_mad_i64_i32 v[54:55], s[2:3], v44, s2, v[66:67]
	v_exp_f32_e32 v66, v37
	v_and_b32_sdwa v37, v59, v195 dst_sel:DWORD dst_unused:UNUSED_PAD src0_sel:WORD_1 src1_sel:DWORD
	v_add3_u32 v37, v59, v37, s33
	v_and_b32_e32 v59, 0xffff0000, v37
	v_mul_f32_e32 v37, 0xbfb8aa3b, v11
	v_exp_f32_e32 v67, v37
	v_and_b32_sdwa v39, v58, v195 dst_sel:DWORD dst_unused:UNUSED_PAD src0_sel:WORD_1 src1_sel:DWORD
	v_add3_u32 v39, v58, v39, s33
	v_and_b32_e32 v58, 0xffff0000, v39
	v_pk_add_f32 v[66:67], v[66:67], 1.0 op_sel_hi:[1,0]
	v_pk_mul_f32 v[56:57], v[56:57], v[52:53]
	v_rcp_f32_e32 v37, v67
	s_nop 0
	v_lshl_add_u64 v[54:55], v[54:55], 0, v[16:17]
	v_fma_f32 v45, -v67, v37, 1.0
	v_fma_f32 v37, v45, v37, v37
	v_mul_f32_e32 v67, v11, v37
	v_rcp_f32_e32 v11, v66
	s_nop 0
	s_nop 0
	v_fma_f32 v39, -v66, v11, 1.0
	v_fma_f32 v11, v39, v11, v11
	v_mul_f32_e32 v66, v6, v11
	v_and_b32_e32 v11, 0xffff0000, v7
	v_lshlrev_b32_e32 v37, 16, v7
	v_and_b32_sdwa v7, v63, v195 dst_sel:DWORD dst_unused:UNUSED_PAD src0_sel:WORD_1 src1_sel:DWORD
	v_add3_u32 v7, v63, v7, s33
	v_mul_f32_e32 v6, 0xbfb8aa3b, v37
	v_and_b32_e32 v63, 0xffff0000, v7
	v_mul_f32_e32 v7, 0xbfb8aa3b, v11
	v_exp_f32_e32 v6, v6
	v_exp_f32_e32 v7, v7
	v_and_b32_sdwa v39, v62, v195 dst_sel:DWORD dst_unused:UNUSED_PAD src0_sel:WORD_1 src1_sel:DWORD
	v_add3_u32 v39, v62, v39, s33
	v_and_b32_e32 v62, 0xffff0000, v39
	v_pk_add_f32 v[6:7], v[6:7], 1.0 op_sel_hi:[1,0]
	v_pk_mul_f32 v[58:59], v[66:67], v[58:59]
	v_rcp_f32_e32 v39, v7
	s_nop 0
	s_nop 0
	v_fma_f32 v66, -v7, v39, 1.0
	v_fma_f32 v39, v66, v39, v39
	v_mul_f32_e32 v7, v11, v39
	v_rcp_f32_e32 v11, v6
	s_nop 0
	s_nop 0
	v_fma_f32 v45, -v6, v11, 1.0
	v_fma_f32 v11, v45, v11, v11
	v_mul_f32_e32 v6, v37, v11
	v_and_b32_e32 v11, 0xffff0000, v8
	v_lshlrev_b32_e32 v8, 16, v8
	v_mul_f32_e32 v37, 0xbfb8aa3b, v8
	v_pk_mul_f32 v[6:7], v[6:7], v[62:63]
	v_exp_f32_e32 v62, v37
	v_and_b32_sdwa v37, v61, v195 dst_sel:DWORD dst_unused:UNUSED_PAD src0_sel:WORD_1 src1_sel:DWORD
	v_add3_u32 v37, v61, v37, s33
	v_and_b32_e32 v61, 0xffff0000, v37
	v_mul_f32_e32 v37, 0xbfb8aa3b, v11
	v_exp_f32_e32 v63, v37
	v_and_b32_sdwa v39, v60, v195 dst_sel:DWORD dst_unused:UNUSED_PAD src0_sel:WORD_1 src1_sel:DWORD
	v_add3_u32 v39, v60, v39, s33
	v_and_b32_e32 v60, 0xffff0000, v39
	v_pk_add_f32 v[62:63], v[62:63], 1.0 op_sel_hi:[1,0]
	s_nop 0
	v_rcp_f32_e32 v37, v63
	s_nop 0
	s_nop 0
	v_fma_f32 v45, -v63, v37, 1.0
	v_fma_f32 v37, v45, v37, v37
	v_mul_f32_e32 v63, v11, v37
	v_rcp_f32_e32 v11, v62
	s_nop 0
	s_nop 0
	v_fma_f32 v39, -v62, v11, 1.0
	v_fma_f32 v11, v39, v11, v11
	v_mul_f32_e32 v62, v8, v11
	v_and_b32_e32 v11, 0xffff0000, v9
	v_lshlrev_b32_e32 v37, 16, v9
	v_and_b32_sdwa v9, v57, v195 dst_sel:DWORD dst_unused:UNUSED_PAD src0_sel:WORD_1 src1_sel:DWORD
	v_add3_u32 v9, v57, v9, s33
	v_mul_f32_e32 v8, 0xbfb8aa3b, v37
	v_and_b32_e32 v57, 0xffff0000, v9
	v_mul_f32_e32 v9, 0xbfb8aa3b, v11
	v_exp_f32_e32 v8, v8
	v_exp_f32_e32 v9, v9
	v_and_b32_sdwa v39, v56, v195 dst_sel:DWORD dst_unused:UNUSED_PAD src0_sel:WORD_1 src1_sel:DWORD
	v_add3_u32 v39, v56, v39, s33
	v_and_b32_e32 v56, 0xffff0000, v39
	v_pk_add_f32 v[8:9], v[8:9], 1.0 op_sel_hi:[1,0]
	v_pk_mul_f32 v[60:61], v[62:63], v[60:61]
	v_rcp_f32_e32 v39, v9
	s_nop 0
	s_nop 0
	v_fma_f32 v62, -v9, v39, 1.0
	v_fma_f32 v39, v62, v39, v39
	v_mul_f32_e32 v9, v11, v39
	v_rcp_f32_e32 v11, v8
	s_nop 0
	s_mov_b64 s[2:3], 0
	v_fma_f32 v45, -v8, v11, 1.0
	v_fma_f32 v11, v45, v11, v11
	v_mul_f32_e32 v8, v37, v11
	v_pk_mul_f32 v[8:9], v[8:9], v[56:57]
	v_bfe_u32 v39, v61, 16, 1
	v_bfe_u32 v11, v9, 16, 1
	v_bfe_u32 v37, v8, 16, 1
	v_bfe_u32 v45, v60, 16, 1
	v_bfe_u32 v56, v7, 16, 1
	v_bfe_u32 v57, v6, 16, 1
	v_bfe_u32 v62, v59, 16, 1
	v_bfe_u32 v63, v58, 16, 1
	v_add3_u32 v58, v58, v63, s33
	v_add3_u32 v59, v59, v62, s33
	v_add3_u32 v6, v6, v57, s33
	v_add3_u32 v7, v7, v56, s33
	v_add3_u32 v45, v60, v45, s33
	v_add3_u32 v39, v61, v39, s33
	v_add3_u32 v8, v8, v37, s33
	v_add3_u32 v9, v9, v11, s33
	v_add_co_u32_e32 v54, vcc, 0x2223c000, v54
	v_perm_b32 v9, v9, v8, s27
	v_perm_b32 v8, v39, v45, s27
	v_perm_b32 v7, v7, v6, s27
	v_perm_b32 v6, v59, v58, s27
	v_addc_co_u32_e32 v55, vcc, 0, v55, vcc
	global_store_dwordx4 v[54:55], v[6:9], off offset:1024

; DEVI float bf2f(u16 h) { return __uint_as_float(((unsigned)h) << 16); }
; DEVI float bfs(short h) { return __uint_as_float(((unsigned)(u16)h) << 16); }
; DEVI float silu_f(float x) { return x / (1.f + __expf(-x)); }
; DEVI void gemm256(const P& p, const u16* A, int lda, const u16* Bt, int ldb, int K, int brow, int bcol, int mode,
;                         int aux, int layer, int bmode) {
;     ...
;     for (int it = 0; it < 16; ++it) {
;       const int R = it * 16 + (tid >> 5), c = tid & 31;
;       if ((c < 16) ? tr0 : tr1) continue;
;       const int row = brow + R, col = bcol + c * 8;
;       bf16x8 raw = *(const bf16x8*)(stg + R * 256 + SWZ(R, c) * 8);
;       if (mode == M_G1A) {
;         *(bf16x8*)((u16*)(ws + O_PROJ) + (size_t)row * NP + col) = raw;
;       } else if (mode == M_G4) {
;         *(bf16x8*)((u16*)(ws + O_YBR) + (size_t)row * 8192 + aux * 2048 + col) = raw;
;       } else {
;         float v[8];
; #pragma unroll
;         for (int e = 0; e < 8; ++e) v[e] = bfs(raw[e]);
;         if (mode == M_G2) {
;           float rs = ((const float*)(ws + O_RINV))[row * 2];
; #pragma unroll
;           for (int e = 0; e < 8; ++e) v[e] *= rs;
;           st8((u16*)(ws + O_QH) + (size_t)row * 768 + col, v);
;         } else if (mode == M_G3) {
;           float rs = ((const float*)(ws + O_RINV))[row * 2 + 1];
; #pragma unroll
;           for (int e = 0; e < 8; ++e) v[e] *= rs;
;           st8((u16*)(ws + O_KH) + ((size_t)(bb * 4 + (col >> 8)) * TPB + (trow + R)) * 192 + (col & 255), v);
;         } else if (mode == M_POOL) {
;           float g[8];
;           ld8((const u16*)(ws + O_PROJ) + (size_t)row * NP + C_BG + col, g);
; #pragma unroll
;           for (int e = 0; e < 8; ++e) {
;             float y = bf2f(f2bf(v[e] * p.pool_scale[layer * 512 + col + e]));
;             v[e] = y * silu_f(g[e]);
;           }
;           st8((u16*)(ws + O_YS) + (size_t)row * 2048 + 512 + col, v);
.LBB0_249:
	s_or_b64 exec, exec, s[34:35]
	s_and_saveexec_b64 s[34:35], s[82:83]
	s_cbranch_execz .LBB0_197
	s_waitcnt lgkmcnt(0)
	ds_read_b128 v[2:5], v0 offset:16384
	v_add_u32_e32 v44, 32, v36
	s_and_b64 vcc, exec, s[40:41]
	s_mov_b64 s[2:3], -1
	s_cbranch_vccnz .LBB0_265
	s_andn2_b64 vcc, exec, s[78:79]
	s_cbranch_vccnz .LBB0_272
	s_waitcnt lgkmcnt(0)
	v_and_b32_e32 v47, 0xffff0000, v2
	v_lshlrev_b32_e32 v46, 16, v2
	v_and_b32_e32 v49, 0xffff0000, v3
	v_lshlrev_b32_e32 v48, 16, v3
	v_and_b32_e32 v51, 0xffff0000, v4
	v_lshlrev_b32_e32 v50, 16, v4
	v_and_b32_e32 v53, 0xffff0000, v5
	v_lshlrev_b32_e32 v52, 16, v5
	s_mov_b64 s[76:77], -1
	s_mov_b64 s[36:37], 0
	s_cmp_lt_i32 s71, 2
	s_mov_b64 s[2:3], 0
	s_cbranch_scc1 .LBB0_267
	s_cmp_gt_i32 s71, 2
	s_cbranch_scc0 .LBB0_257
	s_cmp_eq_u32 s71, 3
	s_mov_b64 s[2:3], -1
	s_cbranch_scc0 .LBB0_256
	v_mov_b64_e32 v[6:7], s[80:81]
	s_movk_i32 s2, 0x3a00
	v_mad_i64_i32 v[66:67], s[2:3], v44, s2, v[6:7]
	v_lshl_add_u64 v[6:7], v[66:67], 0, v[16:17]
	v_add_co_u32_e32 v6, vcc, 0xa28b000, v6
	s_movk_i32 s2, 0xd600
	s_nop 0
	v_addc_co_u32_e32 v7, vcc, 0, v7, vcc
	global_load_dwordx4 v[6:9], v[6:7], off offset:1024
	s_nop 0
	global_load_dwordx4 v[54:57], v[30:31], off offset:16
	global_load_dwordx4 v[58:61], v[30:31], off
	s_waitcnt vmcnt(2)
	v_and_b32_e32 v11, 0xffff0000, v6
	v_lshlrev_b32_e32 v6, 16, v6
	s_waitcnt vmcnt(0)
	v_pk_mul_f32 v[58:59], v[58:59], v[46:47]
	v_mul_f32_e32 v37, 0xbfb8aa3b, v6
	v_pk_mul_f32 v[62:63], v[60:61], v[48:49]
	v_pk_mul_f32 v[60:61], v[54:55], v[50:51]
	v_mad_i64_i32 v[54:55], s[2:3], v44, s2, v[66:67]
	v_exp_f32_e32 v66, v37
	v_and_b32_sdwa v37, v59, v195 dst_sel:DWORD dst_unused:UNUSED_PAD src0_sel:WORD_1 src1_sel:DWORD
	v_add3_u32 v37, v59, v37, s33
	v_and_b32_e32 v59, 0xffff0000, v37
	v_mul_f32_e32 v37, 0xbfb8aa3b, v11
	v_exp_f32_e32 v67, v37
	v_and_b32_sdwa v39, v58, v195 dst_sel:DWORD dst_unused:UNUSED_PAD src0_sel:WORD_1 src1_sel:DWORD
	v_add3_u32 v39, v58, v39, s33
	v_and_b32_e32 v58, 0xffff0000, v39
	v_pk_add_f32 v[66:67], v[66:67], 1.0 op_sel_hi:[1,0]
	v_pk_mul_f32 v[56:57], v[56:57], v[52:53]
	v_rcp_f32_e32 v37, v67
	s_nop 0
	v_lshl_add_u64 v[54:55], v[54:55], 0, v[16:17]
	v_fma_f32 v45, -v67, v37, 1.0
	v_fma_f32 v37, v45, v37, v37
	v_mul_f32_e32 v67, v11, v37
	v_rcp_f32_e32 v11, v66
	s_nop 0
	s_nop 0
	v_fma_f32 v39, -v66, v11, 1.0
	v_fma_f32 v11, v39, v11, v11
	v_mul_f32_e32 v66, v6, v11
	v_and_b32_e32 v11, 0xffff0000, v7
	v_lshlrev_b32_e32 v37, 16, v7
	v_and_b32_sdwa v7, v63, v195 dst_sel:DWORD dst_unused:UNUSED_PAD src0_sel:WORD_1 src1_sel:DWORD
	v_add3_u32 v7, v63, v7, s33
	v_mul_f32_e32 v6, 0xbfb8aa3b, v37
	v_and_b32_e32 v63, 0xffff0000, v7
	v_mul_f32_e32 v7, 0xbfb8aa3b, v11
	v_exp_f32_e32 v6, v6
	v_exp_f32_e32 v7, v7
	v_and_b32_sdwa v39, v62, v195 dst_sel:DWORD dst_unused:UNUSED_PAD src0_sel:WORD_1 src1_sel:DWORD
	v_add3_u32 v39, v62, v39, s33
	v_and_b32_e32 v62, 0xffff0000, v39
	v_pk_add_f32 v[6:7], v[6:7], 1.0 op_sel_hi:[1,0]
	v_pk_mul_f32 v[58:59], v[66:67], v[58:59]
	v_rcp_f32_e32 v39, v7
	s_nop 0
	s_nop 0
	v_fma_f32 v66, -v7, v39, 1.0
	v_fma_f32 v39, v66, v39, v39
	v_mul_f32_e32 v7, v11, v39
	v_rcp_f32_e32 v11, v6
	s_nop 0
	s_nop 0
	v_fma_f32 v45, -v6, v11, 1.0
	v_fma_f32 v11, v45, v11, v11
	v_mul_f32_e32 v6, v37, v11
	v_and_b32_e32 v11, 0xffff0000, v8
	v_lshlrev_b32_e32 v8, 16, v8
	v_mul_f32_e32 v37, 0xbfb8aa3b, v8
	v_pk_mul_f32 v[6:7], v[6:7], v[62:63]
	v_exp_f32_e32 v62, v37
	v_and_b32_sdwa v37, v61, v195 dst_sel:DWORD dst_unused:UNUSED_PAD src0_sel:WORD_1 src1_sel:DWORD
	v_add3_u32 v37, v61, v37, s33
	v_and_b32_e32 v61, 0xffff0000, v37
	v_mul_f32_e32 v37, 0xbfb8aa3b, v11
	v_exp_f32_e32 v63, v37
	v_and_b32_sdwa v39, v60, v195 dst_sel:DWORD dst_unused:UNUSED_PAD src0_sel:WORD_1 src1_sel:DWORD
	v_add3_u32 v39, v60, v39, s33
	v_and_b32_e32 v60, 0xffff0000, v39
	v_pk_add_f32 v[62:63], v[62:63], 1.0 op_sel_hi:[1,0]
	s_nop 0
	v_rcp_f32_e32 v37, v63
	s_nop 0
	s_nop 0
	v_fma_f32 v45, -v63, v37, 1.0
	v_fma_f32 v37, v45, v37, v37
	v_mul_f32_e32 v63, v11, v37
	v_rcp_f32_e32 v11, v62
	s_nop 0
	s_nop 0
	v_fma_f32 v39, -v62, v11, 1.0
	v_fma_f32 v11, v39, v11, v11
	v_mul_f32_e32 v62, v8, v11
	v_and_b32_e32 v11, 0xffff0000, v9
	v_lshlrev_b32_e32 v37, 16, v9
	v_and_b32_sdwa v9, v57, v195 dst_sel:DWORD dst_unused:UNUSED_PAD src0_sel:WORD_1 src1_sel:DWORD
	v_add3_u32 v9, v57, v9, s33
	v_mul_f32_e32 v8, 0xbfb8aa3b, v37
	v_and_b32_e32 v57, 0xffff0000, v9
	v_mul_f32_e32 v9, 0xbfb8aa3b, v11
	v_exp_f32_e32 v8, v8
	v_exp_f32_e32 v9, v9
	v_and_b32_sdwa v39, v56, v195 dst_sel:DWORD dst_unused:UNUSED_PAD src0_sel:WORD_1 src1_sel:DWORD
	v_add3_u32 v39, v56, v39, s33
	v_and_b32_e32 v56, 0xffff0000, v39
	v_pk_add_f32 v[8:9], v[8:9], 1.0 op_sel_hi:[1,0]
	v_pk_mul_f32 v[60:61], v[62:63], v[60:61]
	v_rcp_f32_e32 v39, v9
	s_nop 0
	s_nop 0
	v_fma_f32 v62, -v9, v39, 1.0
	v_fma_f32 v39, v62, v39, v39
	v_mul_f32_e32 v9, v11, v39
	v_rcp_f32_e32 v11, v8
	s_nop 0
	s_mov_b64 s[2:3], 0
	v_fma_f32 v45, -v8, v11, 1.0
	v_fma_f32 v11, v45, v11, v11
	v_mul_f32_e32 v8, v37, v11
	v_pk_mul_f32 v[8:9], v[8:9], v[56:57]
	v_bfe_u32 v39, v61, 16, 1
	v_bfe_u32 v11, v9, 16, 1
	v_bfe_u32 v37, v8, 16, 1
	v_bfe_u32 v45, v60, 16, 1
	v_bfe_u32 v56, v7, 16, 1
	v_bfe_u32 v57, v6, 16, 1
	v_bfe_u32 v62, v59, 16, 1
	v_bfe_u32 v63, v58, 16, 1
	v_add3_u32 v58, v58, v63, s33
	v_add3_u32 v59, v59, v62, s33
	v_add3_u32 v6, v6, v57, s33
	v_add3_u32 v7, v7, v56, s33
	v_add3_u32 v45, v60, v45, s33
	v_add3_u32 v39, v61, v39, s33
	v_add3_u32 v8, v8, v37, s33
	v_add3_u32 v9, v9, v11, s33
	v_add_co_u32_e32 v54, vcc, 0x2223c000, v54
	v_perm_b32 v9, v9, v8, s27
	v_perm_b32 v8, v39, v45, s27
	v_perm_b32 v7, v7, v6, s27
	v_perm_b32 v6, v59, v58, s27
	v_addc_co_u32_e32 v55, vcc, 0, v55, vcc
	global_store_dwordx4 v[54:55], v[6:9], off offset:1024

; DEVI float bf2f(u16 h) { return __uint_as_float(((unsigned)h) << 16); }
; DEVI float bfs(short h) { return __uint_as_float(((unsigned)(u16)h) << 16); }
; DEVI float silu_f(float x) { return x / (1.f + __expf(-x)); }
; DEVI void gemm256(const P& p, const u16* A, int lda, const u16* Bt, int ldb, int K, int brow, int bcol, int mode,
;                         int aux, int layer, int bmode) {
;     ...
;     for (int it = 0; it < 16; ++it) {
;       const int R = it * 16 + (tid >> 5), c = tid & 31;
;       if ((c < 16) ? tr0 : tr1) continue;
;       const int row = brow + R, col = bcol + c * 8;
;       bf16x8 raw = *(const bf16x8*)(stg + R * 256 + SWZ(R, c) * 8);
;       if (mode == M_G1A) {
;         *(bf16x8*)((u16*)(ws + O_PROJ) + (size_t)row * NP + col) = raw;
;       } else if (mode == M_G4) {
;         *(bf16x8*)((u16*)(ws + O_YBR) + (size_t)row * 8192 + aux * 2048 + col) = raw;
;       } else {
;         float v[8];
; #pragma unroll
;         for (int e = 0; e < 8; ++e) v[e] = bfs(raw[e]);
;         if (mode == M_G2) {
;           float rs = ((const float*)(ws + O_RINV))[row * 2];
; #pragma unroll
;           for (int e = 0; e < 8; ++e) v[e] *= rs;
;           st8((u16*)(ws + O_QH) + (size_t)row * 768 + col, v);
;         } else if (mode == M_G3) {
;           float rs = ((const float*)(ws + O_RINV))[row * 2 + 1];
; #pragma unroll
;           for (int e = 0; e < 8; ++e) v[e] *= rs;
;           st8((u16*)(ws + O_KH) + ((size_t)(bb * 4 + (col >> 8)) * TPB + (trow + R)) * 192 + (col & 255), v);
;         } else if (mode == M_POOL) {
;           float g[8];
;           ld8((const u16*)(ws + O_PROJ) + (size_t)row * NP + C_BG + col, g);
; #pragma unroll
;           for (int e = 0; e < 8; ++e) {
;             float y = bf2f(f2bf(v[e] * p.pool_scale[layer * 512 + col + e]));
;             v[e] = y * silu_f(g[e]);
;           }
;           st8((u16*)(ws + O_YS) + (size_t)row * 2048 + 512 + col, v);
.LBB0_276:
	s_waitcnt lgkmcnt(0)
	ds_read_b128 v[2:5], v0 offset:24576
	v_add_u32_e32 v44, 48, v36
	s_and_b64 vcc, exec, s[40:41]
	s_mov_b64 s[2:3], -1
	s_cbranch_vccnz .LBB0_299
	s_andn2_b64 vcc, exec, s[78:79]
	s_cbranch_vccnz .LBB0_296
	s_waitcnt lgkmcnt(0)
	v_and_b32_e32 v47, 0xffff0000, v2
	v_lshlrev_b32_e32 v46, 16, v2
	v_and_b32_e32 v49, 0xffff0000, v3
	v_lshlrev_b32_e32 v48, 16, v3
	v_and_b32_e32 v51, 0xffff0000, v4
	v_lshlrev_b32_e32 v50, 16, v4
	v_and_b32_e32 v53, 0xffff0000, v5
	v_lshlrev_b32_e32 v52, 16, v5
	s_mov_b64 s[76:77], -1
	s_mov_b64 s[36:37], 0
	s_cmp_lt_i32 s71, 2
	s_mov_b64 s[2:3], 0
	s_cbranch_scc1 .LBB0_291
	s_cmp_gt_i32 s71, 2
	s_cbranch_scc0 .LBB0_283
	s_cmp_eq_u32 s71, 3
	s_mov_b64 s[2:3], -1
	s_cbranch_scc0 .LBB0_282
	v_mov_b64_e32 v[6:7], s[80:81]
	s_movk_i32 s2, 0x3a00
	v_mad_i64_i32 v[66:67], s[2:3], v44, s2, v[6:7]
	v_lshl_add_u64 v[6:7], v[66:67], 0, v[16:17]
	v_add_co_u32_e32 v6, vcc, 0xa28b000, v6
	s_movk_i32 s2, 0xd600
	s_nop 0
	v_addc_co_u32_e32 v7, vcc, 0, v7, vcc
	global_load_dwordx4 v[6:9], v[6:7], off offset:1024
	s_nop 0
	global_load_dwordx4 v[54:57], v[30:31], off offset:16
	global_load_dwordx4 v[58:61], v[30:31], off
	s_waitcnt vmcnt(2)
	v_and_b32_e32 v11, 0xffff0000, v6
	v_lshlrev_b32_e32 v6, 16, v6
	s_waitcnt vmcnt(0)
	v_pk_mul_f32 v[58:59], v[58:59], v[46:47]
	v_mul_f32_e32 v37, 0xbfb8aa3b, v6
	v_pk_mul_f32 v[62:63], v[60:61], v[48:49]
	v_pk_mul_f32 v[60:61], v[54:55], v[50:51]
	v_mad_i64_i32 v[54:55], s[2:3], v44, s2, v[66:67]
	v_exp_f32_e32 v66, v37
	v_and_b32_sdwa v37, v59, v195 dst_sel:DWORD dst_unused:UNUSED_PAD src0_sel:WORD_1 src1_sel:DWORD
	v_add3_u32 v37, v59, v37, s33
	v_and_b32_e32 v59, 0xffff0000, v37
	v_mul_f32_e32 v37, 0xbfb8aa3b, v11
	v_exp_f32_e32 v67, v37
	v_and_b32_sdwa v39, v58, v195 dst_sel:DWORD dst_unused:UNUSED_PAD src0_sel:WORD_1 src1_sel:DWORD
	v_add3_u32 v39, v58, v39, s33
	v_and_b32_e32 v58, 0xffff0000, v39
	v_pk_add_f32 v[66:67], v[66:67], 1.0 op_sel_hi:[1,0]
	v_pk_mul_f32 v[56:57], v[56:57], v[52:53]
	v_rcp_f32_e32 v37, v67
	s_nop 0
	v_lshl_add_u64 v[54:55], v[54:55], 0, v[16:17]
	v_fma_f32 v45, -v67, v37, 1.0
	v_fma_f32 v37, v45, v37, v37
	v_mul_f32_e32 v67, v11, v37
	v_rcp_f32_e32 v11, v66
	s_nop 0
	s_nop 0
	v_fma_f32 v39, -v66, v11, 1.0
	v_fma_f32 v11, v39, v11, v11
	v_mul_f32_e32 v66, v6, v11
	v_and_b32_e32 v11, 0xffff0000, v7
	v_lshlrev_b32_e32 v37, 16, v7
	v_and_b32_sdwa v7, v63, v195 dst_sel:DWORD dst_unused:UNUSED_PAD src0_sel:WORD_1 src1_sel:DWORD
	v_add3_u32 v7, v63, v7, s33
	v_mul_f32_e32 v6, 0xbfb8aa3b, v37
	v_and_b32_e32 v63, 0xffff0000, v7
	v_mul_f32_e32 v7, 0xbfb8aa3b, v11
	v_exp_f32_e32 v6, v6
	v_exp_f32_e32 v7, v7
	v_and_b32_sdwa v39, v62, v195 dst_sel:DWORD dst_unused:UNUSED_PAD src0_sel:WORD_1 src1_sel:DWORD
	v_add3_u32 v39, v62, v39, s33
	v_and_b32_e32 v62, 0xffff0000, v39
	v_pk_add_f32 v[6:7], v[6:7], 1.0 op_sel_hi:[1,0]
	v_pk_mul_f32 v[58:59], v[66:67], v[58:59]
	v_rcp_f32_e32 v39, v7
	s_nop 0
	s_nop 0
	v_fma_f32 v66, -v7, v39, 1.0
	v_fma_f32 v39, v66, v39, v39
	v_mul_f32_e32 v7, v11, v39
	v_rcp_f32_e32 v11, v6
	s_nop 0
	s_nop 0
	v_fma_f32 v45, -v6, v11, 1.0
	v_fma_f32 v11, v45, v11, v11
	v_mul_f32_e32 v6, v37, v11
	v_and_b32_e32 v11, 0xffff0000, v8
	v_lshlrev_b32_e32 v8, 16, v8
	v_mul_f32_e32 v37, 0xbfb8aa3b, v8
	v_pk_mul_f32 v[6:7], v[6:7], v[62:63]
	v_exp_f32_e32 v62, v37
	v_and_b32_sdwa v37, v61, v195 dst_sel:DWORD dst_unused:UNUSED_PAD src0_sel:WORD_1 src1_sel:DWORD
	v_add3_u32 v37, v61, v37, s33
	v_and_b32_e32 v61, 0xffff0000, v37
	v_mul_f32_e32 v37, 0xbfb8aa3b, v11
	v_exp_f32_e32 v63, v37
	v_and_b32_sdwa v39, v60, v195 dst_sel:DWORD dst_unused:UNUSED_PAD src0_sel:WORD_1 src1_sel:DWORD
	v_add3_u32 v39, v60, v39, s33
	v_and_b32_e32 v60, 0xffff0000, v39
	v_pk_add_f32 v[62:63], v[62:63], 1.0 op_sel_hi:[1,0]
	s_nop 0
	v_rcp_f32_e32 v37, v63
	s_nop 0
	s_nop 0
	v_fma_f32 v45, -v63, v37, 1.0
	v_fma_f32 v37, v45, v37, v37
	v_mul_f32_e32 v63, v11, v37
	v_rcp_f32_e32 v11, v62
	s_nop 0
	s_nop 0
	v_fma_f32 v39, -v62, v11, 1.0
	v_fma_f32 v11, v39, v11, v11
	v_mul_f32_e32 v62, v8, v11
	v_and_b32_e32 v11, 0xffff0000, v9
	v_lshlrev_b32_e32 v37, 16, v9
	v_and_b32_sdwa v9, v57, v195 dst_sel:DWORD dst_unused:UNUSED_PAD src0_sel:WORD_1 src1_sel:DWORD
	v_add3_u32 v9, v57, v9, s33
	v_mul_f32_e32 v8, 0xbfb8aa3b, v37
	v_and_b32_e32 v57, 0xffff0000, v9
	v_mul_f32_e32 v9, 0xbfb8aa3b, v11
	v_exp_f32_e32 v8, v8
	v_exp_f32_e32 v9, v9
	v_and_b32_sdwa v39, v56, v195 dst_sel:DWORD dst_unused:UNUSED_PAD src0_sel:WORD_1 src1_sel:DWORD
	v_add3_u32 v39, v56, v39, s33
	v_and_b32_e32 v56, 0xffff0000, v39
	v_pk_add_f32 v[8:9], v[8:9], 1.0 op_sel_hi:[1,0]
	v_pk_mul_f32 v[60:61], v[62:63], v[60:61]
	v_rcp_f32_e32 v39, v9
	s_nop 0
	s_nop 0
	v_fma_f32 v62, -v9, v39, 1.0
	v_fma_f32 v39, v62, v39, v39
	v_mul_f32_e32 v9, v11, v39
	v_rcp_f32_e32 v11, v8
	s_nop 0
	s_mov_b64 s[2:3], 0
	v_fma_f32 v45, -v8, v11, 1.0
	v_fma_f32 v11, v45, v11, v11
	v_mul_f32_e32 v8, v37, v11
	v_pk_mul_f32 v[8:9], v[8:9], v[56:57]
	v_bfe_u32 v39, v61, 16, 1
	v_bfe_u32 v11, v9, 16, 1
	v_bfe_u32 v37, v8, 16, 1
	v_bfe_u32 v45, v60, 16, 1
	v_bfe_u32 v56, v7, 16, 1
	v_bfe_u32 v57, v6, 16, 1
	v_bfe_u32 v62, v59, 16, 1
	v_bfe_u32 v63, v58, 16, 1
	v_add3_u32 v58, v58, v63, s33
	v_add3_u32 v59, v59, v62, s33
	v_add3_u32 v6, v6, v57, s33
	v_add3_u32 v7, v7, v56, s33
	v_add3_u32 v45, v60, v45, s33
	v_add3_u32 v39, v61, v39, s33
	v_add3_u32 v8, v8, v37, s33
	v_add3_u32 v9, v9, v11, s33
	v_add_co_u32_e32 v54, vcc, 0x2223c000, v54
	v_perm_b32 v9, v9, v8, s27
	v_perm_b32 v8, v39, v45, s27
	v_perm_b32 v7, v7, v6, s27
	v_perm_b32 v6, v59, v58, s27
	v_addc_co_u32_e32 v55, vcc, 0, v55, vcc
	global_store_dwordx4 v[54:55], v[6:9], off offset:1024
